# v113 + 4 M-tiles x 8 N-tiles per round in the QK projection GEMM0 too (A = normalised activations read half as often)
# speedup vs baseline: 1.0165x; 1.0030x over previous
; template <int GI>
; __device__ __forceinline__ bool sched_next(unsigned char* ws, int i, int G, int c, GUnit& u) {
;     ...
;     u.SA = 128 * d.ldc; u.SR = d.ldc; u.SB = 128; u.SX = 64; u.scale = d.scale;
;     if (d.kind == 0) {
;         constexpr int nwg = d.nM * d.nN;
;         if (L >= nwg) return false;
;         int wgid = L;
;         { constexpr int q = nwg / 8, r = nwg % 8; const int xcd = wgid % 8, off = wgid / 8; wgid = (xcd < r ? xcd * (q + 1) : r * (q + 1) + (xcd - r) * q) + off; }
;         constexpr int nig = 8 * d.nN; const int gid = wgid / nig, fm = gid * 8, gsz = (d.nM - fm) < 8 ? (d.nM - fm) : 8;
;         const int pm = fm + ((wgid % nig) % gsz), pn = (wgid % nig) / gsz;
;         u.A = (const char*)ws + d.A + (size_t)pm * d.a_tile;
;         u.B = (const char*)ws + d.B + (size_t)(pm >> 4) * d.b_batch + (size_t)pn * d.b_tile;
;         u.C = (char*)ws + d.C + (size_t)pm * d.c_rt + (size_t)pn * d.c_ct;
;         if (d.scale_kind == 1) {
;             u.scale = (pn < 4) ? 0.125f * LOG2E : ((pn >= 8 && pn < 12) ? 0.08838834764831845f * LOG2E : 1.0f);
;             if (pn >= 4 && pn < 8) {
;                 u.C = (char*)ws + WS_KD + ((size_t)(4 * (pn - 4)) * MT + (size_t)pm * 256) * 64 * 2;
;                 u.SA = 128 * 64; u.SR = 64; u.SB = 2 * MT * 64; u.SX = MT * 64;
;             } else if (pn >= 12) {
;                 u.C = (char*)ws + WS_KS + ((size_t)(2 * (pn - 12)) * MT + (size_t)pm * 256) * 128 * 2;
;                 u.SA = 128 * 128; u.SR = 128; u.SB = MT * 128; u.SX = 64;
;             }
.LBB0_72:
	s_ashr_i32 s0, s0, 3
	s_add_i32 s0, s3, s0
	s_and_b32 s1, s0, 3
	s_bfe_u32 s3, s0, 0x10005
	s_lshl_b32 s3, s3, 2
	s_or_b32 s1, s1, s3
	s_bfe_u32 s3, s0, 0x30002
	s_lshl_b32 s3, s3, 3
	s_or_b32 s1, s1, s3
	s_andn2_b32 s0, s0, 63
	s_or_b32 s0, s0, s1
	s_ashr_i32 s1, s0, 31
	s_lshr_b32 s1, s1, 25
	s_add_i32 s1, s0, s1
	s_ashr_i32 s3, s1, 7
	s_and_b32 s1, s1, 0xffffff80
	s_sub_i32 s0, s0, s1
	s_bfe_i32 s1, s0, 0x80000
	s_bfe_u32 s1, s1, 0x3000c
	s_add_i32 s1, s0, s1
	s_bfe_i32 s4, s1, 0x80000
	s_and_b32 s1, s1, 0xf8
	s_sub_i32 s1, s0, s1
	s_lshl_b32 s3, s3, 3
	s_sext_i32_i16 s5, s4
	s_sext_i32_i8 s1, s1
	s_lshr_b32 s4, s5, 3
	s_add_i32 s6, s3, s1
	s_ashr_i32 s1, s5, 3
	s_ashr_i32 s7, s6, 31
	s_bfe_i64 s[4:5], s[4:5], 0x100000
	s_and_b32 s3, s0, 0xffffffe0
	s_cmp_lg_u32 s3, 32
	s_cbranch_scc0 .LBB0_75
	s_lshl_b64 s[12:13], s[6:7], 21
	s_add_u32 s3, s28, s12
	s_addc_u32 s14, s29, s13
	s_lshl_b64 s[12:13], s[4:5], 9
	s_add_u32 s3, s3, s12
	s_addc_u32 s13, s14, s13
	s_add_u32 s12, s3, 0x16000000
	s_addc_u32 s13, s13, 0
	s_cmpk_lt_i32 s0, 0x60
	s_cbranch_scc1 .LBB0_76
	s_lshl_b32 s3, s1, 1
	s_sub_i32 s12, s3, 24
	s_mov_b32 s13, 0
	s_lshl_b64 s[12:13], s[12:13], 23
	s_add_u32 s3, s28, s12
	s_addc_u32 s14, s29, s13
	s_lshl_b64 s[12:13], s[6:7], 16
	s_add_u32 s3, s3, s12
	s_addc_u32 s13, s14, s13
	s_add_u32 s12, s3, 0x3a000000
	s_addc_u32 s13, s13, 0
	s_mov_b64 s[74:75], 0x400000
	s_mov_b64 s[68:69], 0x80
	s_mov_b64 s[38:39], 0x4000
	s_branch .LBB0_77

; template <int GI>
; __device__ __forceinline__ bool sched_next(unsigned char* ws, int i, int G, int c, GUnit& u) {
;     ...
;     u.SA = 128 * d.ldc; u.SR = d.ldc; u.SB = 128; u.SX = 64; u.scale = d.scale;
;     if (d.kind == 0) {
;         constexpr int nwg = d.nM * d.nN;
;         if (L >= nwg) return false;
;         int wgid = L;
;         { constexpr int q = nwg / 8, r = nwg % 8; const int xcd = wgid % 8, off = wgid / 8; wgid = (xcd < r ? xcd * (q + 1) : r * (q + 1) + (xcd - r) * q) + off; }
;         constexpr int nig = 8 * d.nN; const int gid = wgid / nig, fm = gid * 8, gsz = (d.nM - fm) < 8 ? (d.nM - fm) : 8;
;         const int pm = fm + ((wgid % nig) % gsz), pn = (wgid % nig) / gsz;
;         u.A = (const char*)ws + d.A + (size_t)pm * d.a_tile;
;         u.B = (const char*)ws + d.B + (size_t)(pm >> 4) * d.b_batch + (size_t)pn * d.b_tile;
;         u.C = (char*)ws + d.C + (size_t)pm * d.c_rt + (size_t)pn * d.c_ct;
;         if (d.scale_kind == 1) {
;             u.scale = (pn < 4) ? 0.125f * LOG2E : ((pn >= 8 && pn < 12) ? 0.08838834764831845f * LOG2E : 1.0f);
;             if (pn >= 4 && pn < 8) {
;                 u.C = (char*)ws + WS_KD + ((size_t)(4 * (pn - 4)) * MT + (size_t)pm * 256) * 64 * 2;
;                 u.SA = 128 * 64; u.SR = 64; u.SB = 2 * MT * 64; u.SX = MT * 64;
;             } else if (pn >= 12) {
;                 u.C = (char*)ws + WS_KS + ((size_t)(2 * (pn - 12)) * MT + (size_t)pm * 256) * 128 * 2;
;                 u.SA = 128 * 128; u.SR = 128; u.SB = MT * 128; u.SX = 64;
;             }
; template <int GI>
; __device__ __forceinline__ void gemm_phase(LAS unsigned char* lds, unsigned char* ws, int G, int cblk) {
;     ...
;         const bool has_next = sched_next<GI>(ws, ui + 1, G, cblk, nxt);
;         const char* nA = has_next ? nxt.A : cA; const char* nB = has_next ? nxt.B : cB;
.LBB0_90:
	s_ashr_i32 s4, s6, 3
	s_add_i32 s4, s14, s4
	s_and_b32 s5, s4, 3
	s_bfe_u32 s6, s4, 0x10005
	s_lshl_b32 s6, s6, 2
	s_or_b32 s5, s5, s6
	s_bfe_u32 s6, s4, 0x30002
	s_lshl_b32 s6, s6, 3
	s_or_b32 s5, s5, s6
	s_andn2_b32 s4, s4, 63
	s_or_b32 s4, s4, s5
	s_ashr_i32 s5, s4, 31
	s_lshr_b32 s5, s5, 25
	s_add_i32 s5, s4, s5
	s_ashr_i32 s6, s5, 7
	s_and_b32 s5, s5, 0xffffff80
	s_sub_i32 s58, s4, s5
	s_bfe_i32 s4, s58, 0x80000
	s_bfe_u32 s4, s4, 0x3000c
	s_add_i32 s5, s58, s4
	s_bfe_i32 s4, s5, 0x80000
	s_and_b32 s5, s5, 0xf8
	s_sub_i32 s5, s58, s5
	s_lshl_b32 s6, s6, 3
	s_sext_i32_i8 s5, s5
	s_add_i32 s96, s6, s5
	s_sext_i32_i16 s7, s4
	s_ashr_i32 s97, s96, 31
	s_lshr_b32 s4, s7, 3
	s_ashr_i32 s34, s7, 3
	s_lshl_b64 s[6:7], s[96:97], 20
	s_add_u32 s80, s16, s6
	s_addc_u32 s81, s17, s7
	s_bfe_i64 s[14:15], s[4:5], 0x100000
	s_lshl_b64 s[4:5], s[14:15], 20
	s_add_u32 s84, s8, s4
	s_addc_u32 s85, s9, s5
	s_and_b32 s4, s58, 0x7fffffe0
	s_cmp_eq_u32 s4, 64
	s_cselect_b64 s[6:7], -1, 0
	s_cmp_gt_i32 s58, 31
	s_cselect_b64 s[4:5], -1, 0
	s_and_b32 s82, s58, 0xffffffe0
	s_cmp_lg_u32 s82, 32
	s_mov_b64 vcc, -1
	s_cbranch_scc0 .LBB0_93
	s_lshl_b64 s[82:83], s[96:97], 21
	s_add_u32 s82, s22, s82
	s_addc_u32 s83, s23, s83
	s_lshl_b64 s[14:15], s[14:15], 9
	s_add_u32 s82, s82, s14
	s_addc_u32 s83, s83, s15
	s_cmpk_lt_i32 s58, 0x60
	s_cbranch_scc1 .LBB0_104
	s_lshl_b32 s14, s34, 1
	s_sub_i32 s58, s14, 24
	s_lshl_b64 s[14:15], s[58:59], 23
	v_readlane_b32 s58, v245, 29
	s_add_u32 s58, s58, s14
	v_readlane_b32 s14, v245, 30
	s_addc_u32 s83, s14, s15
	s_lshl_b64 s[14:15], s[96:97], 16
	s_add_u32 s82, s58, s14
	s_addc_u32 s83, s83, s15
	s_mov_b64 s[90:91], 0x400000
	s_mov_b64 s[86:87], 0x80
	s_mov_b64 s[88:89], 0x4000
	s_mov_b64 vcc, 0
